# v37 + per-tile decay/stabiliser reference (cvt, fmamk, mul, sub) computed under the QK MFMAs instead of after them; slow and diagonal paths recompute it
# baseline (speedup 1.0000x reference)
.LBB0_510:
	s_add_i32 s49, s63, s25
	s_cmp_lg_u32 s49, 0
	s_waitcnt lgkmcnt(7)
	v_mfma_f32_32x32x16_bf16 v[158:173], v[142:145], v[174:177], v[80:95]
	v_cvt_f32_i32_e32 v0, s49
	s_waitcnt lgkmcnt(6)
	v_mfma_f32_32x32x16_bf16 v[158:173], v[146:149], v[178:181], v[158:173]
	v_fmamk_f32 v0, v0, 0x42800000, v244
	s_waitcnt lgkmcnt(5)
	v_mfma_f32_32x32x16_bf16 v[158:173], v[150:153], v[182:185], v[158:173]
	v_mul_f32_e64 v0, v0, -v226
	s_waitcnt lgkmcnt(4)
	v_mfma_f32_32x32x16_bf16 v[158:173], v[154:157], v[186:189], v[158:173]
	v_sub_f32_e32 v239, v251, v0
	s_waitcnt lgkmcnt(3)
	v_mfma_f32_32x32x16_bf16 v[142:157], v[2:5], v[174:177], v[96:111]
	s_waitcnt lgkmcnt(2)
	v_mfma_f32_32x32x16_bf16 v[142:157], v[6:9], v[178:181], v[142:157]
	s_waitcnt lgkmcnt(1)
	v_mfma_f32_32x32x16_bf16 v[142:157], v[10:13], v[182:185], v[142:157]
	s_waitcnt lgkmcnt(0)
	v_mfma_f32_32x32x16_bf16 v[142:157], v[208:211], v[186:189], v[142:157]
	ds_read_b64_tr_b16 v[2:3], v240 offset:17408
	ds_read_b64_tr_b16 v[4:5], v240 offset:19968
	ds_read_b64_tr_b16 v[6:7], v240 offset:17472
	ds_read_b64_tr_b16 v[8:9], v240 offset:20032
	ds_read_b64_tr_b16 v[10:11], v240 offset:17536
	ds_read_b64_tr_b16 v[12:13], v240 offset:20096
	ds_read_b64_tr_b16 v[208:209], v240 offset:17600
	ds_read_b64_tr_b16 v[210:211], v240 offset:20160
	ds_read_b64_tr_b16 v[212:213], v240 offset:22528
	ds_read_b64_tr_b16 v[214:215], v240 offset:25088
	s_cbranch_scc0 .LBB0_512
	s_cmp_eq_u32 s100, 0
	s_cbranch_scc1 .LBB0_515
	s_branch .LBB0_513

.Lattn_ref_fix:
	v_sub_f32_e32 v239, v251, v0
.LBB0_515:
	v_sub_f32_e32 v158, v158, v239
	v_sub_f32_e32 v159, v159, v239
	v_exp_f32_e32 v158, v158
	v_exp_f32_e32 v159, v159
	v_sub_f32_e32 v160, v160, v239
	v_sub_f32_e32 v161, v161, v239
	v_add_f32_e32 v14, 0, v158
	v_add_f32_e32 v15, 0, v159
	v_cvt_pk_bf16_f32 v158, v158, v159
	v_exp_f32_e32 v160, v160
	v_exp_f32_e32 v161, v161
	v_sub_f32_e32 v162, v162, v239
	v_sub_f32_e32 v163, v163, v239
	v_add_f32_e32 v14, v160, v14
	v_add_f32_e32 v15, v161, v15
	v_cvt_pk_bf16_f32 v159, v160, v161
	v_exp_f32_e32 v162, v162
	v_exp_f32_e32 v163, v163
	v_sub_f32_e32 v164, v164, v239
	v_sub_f32_e32 v165, v165, v239
	v_add_f32_e32 v14, v162, v14
	v_add_f32_e32 v15, v163, v15
	v_cvt_pk_bf16_f32 v160, v162, v163
	v_exp_f32_e32 v164, v164
	v_exp_f32_e32 v165, v165
	v_sub_f32_e32 v166, v166, v239
	v_sub_f32_e32 v167, v167, v239
	v_add_f32_e32 v14, v164, v14
	v_add_f32_e32 v15, v165, v15
	v_cvt_pk_bf16_f32 v161, v164, v165
	ds_read_b64_tr_b16 v[162:163], v240 offset:22592
	ds_read_b64_tr_b16 v[164:165], v240 offset:25152
	s_waitcnt lgkmcnt(10)
	v_mfma_f32_32x32x16_bf16 v[64:79], v[2:5], v[158:161], v[64:79]
	ds_read_b64_tr_b16 v[2:3], v240 offset:22656
	ds_read_b64_tr_b16 v[4:5], v240 offset:25216
	v_exp_f32_e32 v166, v166
	v_exp_f32_e32 v167, v167
	v_sub_f32_e32 v168, v168, v239
	v_sub_f32_e32 v169, v169, v239
	v_add_f32_e32 v14, v166, v14
	v_add_f32_e32 v15, v167, v15
	v_cvt_pk_bf16_f32 v166, v166, v167
	s_waitcnt lgkmcnt(10)
	v_mfma_f32_32x32x16_bf16 v[48:63], v[6:9], v[158:161], v[48:63]
	ds_read_b64_tr_b16 v[6:7], v240 offset:22720
	ds_read_b64_tr_b16 v[8:9], v240 offset:25280
	v_exp_f32_e32 v168, v168
	v_exp_f32_e32 v169, v169
	v_sub_f32_e32 v170, v170, v239
	v_sub_f32_e32 v171, v171, v239
	v_add_f32_e32 v14, v168, v14
	v_add_f32_e32 v15, v169, v15
	v_cvt_pk_bf16_f32 v167, v168, v169
	s_waitcnt lgkmcnt(10)
	v_mfma_f32_32x32x16_bf16 v[32:47], v[10:13], v[158:161], v[32:47]
	ds_read_b64_tr_b16 v[10:11], v240 offset:27648
	ds_read_b64_tr_b16 v[12:13], v240 offset:30208
	v_exp_f32_e32 v170, v170
	v_exp_f32_e32 v171, v171
	v_sub_f32_e32 v172, v172, v239
	v_sub_f32_e32 v173, v173, v239
	v_add_f32_e32 v14, v170, v14
	v_add_f32_e32 v15, v171, v15
	v_cvt_pk_bf16_f32 v168, v170, v171
	s_waitcnt lgkmcnt(10)
	v_mfma_f32_32x32x16_bf16 v[16:31], v[208:211], v[158:161], v[16:31]
	ds_read_b64_tr_b16 v[208:209], v240 offset:27712
	ds_read_b64_tr_b16 v[210:211], v240 offset:30272
	v_exp_f32_e32 v172, v172
	v_exp_f32_e32 v173, v173
	v_sub_f32_e32 v142, v142, v239
	v_sub_f32_e32 v143, v143, v239
	v_add_f32_e32 v14, v172, v14
	v_add_f32_e32 v15, v173, v15
	v_cvt_pk_bf16_f32 v169, v172, v173
	ds_read_b64_tr_b16 v[170:171], v240 offset:27776
	ds_read_b64_tr_b16 v[172:173], v240 offset:30336
	s_waitcnt lgkmcnt(12)
	v_mfma_f32_32x32x16_bf16 v[64:79], v[212:215], v[166:169], v[64:79]
	ds_read_b64_tr_b16 v[212:213], v240 offset:27840
	ds_read_b64_tr_b16 v[214:215], v240 offset:30400
	v_exp_f32_e32 v142, v142
	v_exp_f32_e32 v143, v143
	v_sub_f32_e32 v144, v144, v239
	v_sub_f32_e32 v145, v145, v239
	v_add_f32_e32 v14, v142, v14
	v_add_f32_e32 v15, v143, v15
	v_cvt_pk_bf16_f32 v142, v142, v143
	s_waitcnt lgkmcnt(12)
	v_mfma_f32_32x32x16_bf16 v[48:63], v[162:165], v[166:169], v[48:63]
	ds_read_b64_tr_b16 v[162:163], v240 offset:32768
	ds_read_b64_tr_b16 v[164:165], v240 offset:35328
	v_exp_f32_e32 v144, v144
	v_exp_f32_e32 v145, v145
	v_sub_f32_e32 v146, v146, v239
	v_sub_f32_e32 v147, v147, v239
	v_add_f32_e32 v14, v144, v14
	v_add_f32_e32 v15, v145, v15
	v_cvt_pk_bf16_f32 v143, v144, v145
	s_waitcnt lgkmcnt(12)
	v_mfma_f32_32x32x16_bf16 v[32:47], v[2:5], v[166:169], v[32:47]
	ds_read_b64_tr_b16 v[2:3], v240 offset:32832
	ds_read_b64_tr_b16 v[4:5], v240 offset:35392
	v_exp_f32_e32 v146, v146
	v_exp_f32_e32 v147, v147
	v_sub_f32_e32 v148, v148, v239
	v_sub_f32_e32 v149, v149, v239
	v_add_f32_e32 v14, v146, v14
	v_add_f32_e32 v15, v147, v15
	v_cvt_pk_bf16_f32 v144, v146, v147
	s_waitcnt lgkmcnt(12)
	v_mfma_f32_32x32x16_bf16 v[16:31], v[6:9], v[166:169], v[16:31]
	ds_read_b64_tr_b16 v[6:7], v240 offset:32896
	ds_read_b64_tr_b16 v[8:9], v240 offset:35456
	v_exp_f32_e32 v148, v148
	v_exp_f32_e32 v149, v149
	v_sub_f32_e32 v150, v150, v239
	v_sub_f32_e32 v151, v151, v239
	v_add_f32_e32 v14, v148, v14
	v_add_f32_e32 v15, v149, v15
	v_cvt_pk_bf16_f32 v145, v148, v149
	ds_read_b64_tr_b16 v[146:147], v240 offset:32960
	ds_read_b64_tr_b16 v[148:149], v240 offset:35520
	s_waitcnt lgkmcnt(14)
	v_mfma_f32_32x32x16_bf16 v[64:79], v[10:13], v[142:145], v[64:79]
	v_exp_f32_e32 v150, v150
	v_exp_f32_e32 v151, v151
	v_sub_f32_e32 v152, v152, v239
	v_sub_f32_e32 v153, v153, v239
	v_add_f32_e32 v14, v150, v14
	v_add_f32_e32 v15, v151, v15
	v_cvt_pk_bf16_f32 v150, v150, v151
	s_waitcnt lgkmcnt(12)
	v_mfma_f32_32x32x16_bf16 v[48:63], v[208:211], v[142:145], v[48:63]
	v_exp_f32_e32 v152, v152
	v_exp_f32_e32 v153, v153
	v_sub_f32_e32 v154, v154, v239
	v_sub_f32_e32 v155, v155, v239
	v_add_f32_e32 v14, v152, v14
	v_add_f32_e32 v15, v153, v15
	v_cvt_pk_bf16_f32 v151, v152, v153
	s_waitcnt lgkmcnt(10)
	v_mfma_f32_32x32x16_bf16 v[32:47], v[170:173], v[142:145], v[32:47]
	v_exp_f32_e32 v154, v154
	v_exp_f32_e32 v155, v155
	v_sub_f32_e32 v156, v156, v239
	v_sub_f32_e32 v157, v157, v239
	v_add_f32_e32 v14, v154, v14
	v_add_f32_e32 v15, v155, v15
	v_cvt_pk_bf16_f32 v152, v154, v155
	s_waitcnt lgkmcnt(8)
	v_mfma_f32_32x32x16_bf16 v[16:31], v[212:215], v[142:145], v[16:31]
	v_exp_f32_e32 v156, v156
	v_exp_f32_e32 v157, v157
	s_nop 0
	v_add_f32_e32 v14, v156, v14
	v_add_f32_e32 v15, v157, v15
	v_cvt_pk_bf16_f32 v153, v156, v157
	v_add_f32_e32 v14, v14, v15
	v_add_f32_e32 v250, v250, v14
	s_andn2_b64 vcc, exec, s[20:21]
	s_cbranch_vccnz .Lattn_pv3_nostore
	s_andn2_b32 s101, 1, s25
	s_mul_i32 s101, s101, 0x9400
	v_add_u32_e32 v14, s101, v221
	v_add_u32_e32 v15, v14, v242
	v_add_u32_e32 v239, v14, v241
	v_add_u32_e32 v252, v14, v225
	v_add_u32_e32 v14, v14, v223
	s_waitcnt vmcnt(3)
	ds_write_b128 v14, v[190:193]
	s_waitcnt vmcnt(2)
	ds_write_b128 v239, v[198:201]
	s_waitcnt vmcnt(1)
	ds_write_b128 v252, v[194:197] offset:17408
	s_waitcnt vmcnt(0)
	ds_write_b128 v15, v[202:205] offset:17408
	s_waitcnt lgkmcnt(10)
	v_mfma_f32_32x32x16_bf16 v[64:79], v[162:165], v[150:153], v[64:79]
	s_waitcnt lgkmcnt(8)
	v_mfma_f32_32x32x16_bf16 v[48:63], v[2:5], v[150:153], v[48:63]
	s_waitcnt lgkmcnt(6)
	v_mfma_f32_32x32x16_bf16 v[32:47], v[6:9], v[150:153], v[32:47]
	s_waitcnt lgkmcnt(4)
	v_mfma_f32_32x32x16_bf16 v[16:31], v[146:149], v[150:153], v[16:31]
	s_branch .LBB0_505
